# cmp pass 2 far loop: second quad exchange folded into one DPP add per group (3 fewer issue slots x 8 groups per block, same sums)
# speedup vs baseline: 1.0011x; 1.0003x over previous
.Lc2_k:
	v_add_u32_e32 v91, s18, v72
	s_nop 1
	v_pk_fma_f32 v[2:3], v[2:3], s[28:29], v[208:209] op_sel_hi:[1,0,1]
	v_pk_fma_f32 v[4:5], v[4:5], s[28:29], v[208:209] op_sel_hi:[1,0,1]
	v_pk_fma_f32 v[6:7], v[6:7], s[28:29], v[208:209] op_sel_hi:[1,0,1]
	v_pk_fma_f32 v[8:9], v[8:9], s[28:29], v[208:209] op_sel_hi:[1,0,1]
	v_pk_fma_f32 v[10:11], v[10:11], s[28:29], v[208:209] op_sel_hi:[1,0,1]
	v_pk_fma_f32 v[12:13], v[12:13], s[28:29], v[208:209] op_sel_hi:[1,0,1]
	v_pk_fma_f32 v[14:15], v[14:15], s[28:29], v[208:209] op_sel_hi:[1,0,1]
	v_pk_fma_f32 v[16:17], v[16:17], s[28:29], v[208:209] op_sel_hi:[1,0,1]
	v_pk_fma_f32 v[18:19], v[18:19], s[28:29], v[208:209] op_sel_hi:[1,0,1]
	v_pk_fma_f32 v[20:21], v[20:21], s[28:29], v[208:209] op_sel_hi:[1,0,1]
	v_pk_fma_f32 v[22:23], v[22:23], s[28:29], v[208:209] op_sel_hi:[1,0,1]
	v_pk_fma_f32 v[24:25], v[24:25], s[28:29], v[208:209] op_sel_hi:[1,0,1]
	v_pk_fma_f32 v[26:27], v[26:27], s[28:29], v[208:209] op_sel_hi:[1,0,1]
	v_pk_fma_f32 v[28:29], v[28:29], s[28:29], v[208:209] op_sel_hi:[1,0,1]
	v_pk_fma_f32 v[30:31], v[30:31], s[28:29], v[208:209] op_sel_hi:[1,0,1]
	v_pk_fma_f32 v[32:33], v[32:33], s[28:29], v[208:209] op_sel_hi:[1,0,1]
	v_pk_add_f32 v[2:3], v[2:3], v[76:77] op_sel_hi:[1,0] neg_lo:[0,1] neg_hi:[0,1]
	v_pk_add_f32 v[4:5], v[4:5], v[76:77] op_sel_hi:[1,0] neg_lo:[0,1] neg_hi:[0,1]
	v_pk_add_f32 v[6:7], v[6:7], v[76:77] op_sel_hi:[1,0] neg_lo:[0,1] neg_hi:[0,1]
	v_pk_add_f32 v[8:9], v[8:9], v[76:77] op_sel_hi:[1,0] neg_lo:[0,1] neg_hi:[0,1]
	v_pk_add_f32 v[10:11], v[10:11], v[76:77] op_sel_hi:[1,0] neg_lo:[0,1] neg_hi:[0,1]
	v_pk_add_f32 v[12:13], v[12:13], v[76:77] op_sel_hi:[1,0] neg_lo:[0,1] neg_hi:[0,1]
	v_pk_add_f32 v[14:15], v[14:15], v[76:77] op_sel_hi:[1,0] neg_lo:[0,1] neg_hi:[0,1]
	v_pk_add_f32 v[16:17], v[16:17], v[76:77] op_sel_hi:[1,0] neg_lo:[0,1] neg_hi:[0,1]
	v_pk_add_f32 v[18:19], v[18:19], v[76:77] op_sel_hi:[1,0] neg_lo:[0,1] neg_hi:[0,1]
	v_pk_add_f32 v[20:21], v[20:21], v[76:77] op_sel_hi:[1,0] neg_lo:[0,1] neg_hi:[0,1]
	v_pk_add_f32 v[22:23], v[22:23], v[76:77] op_sel_hi:[1,0] neg_lo:[0,1] neg_hi:[0,1]
	v_pk_add_f32 v[24:25], v[24:25], v[76:77] op_sel_hi:[1,0] neg_lo:[0,1] neg_hi:[0,1]
	v_pk_add_f32 v[26:27], v[26:27], v[76:77] op_sel_hi:[1,0] neg_lo:[0,1] neg_hi:[0,1]
	v_pk_add_f32 v[28:29], v[28:29], v[76:77] op_sel_hi:[1,0] neg_lo:[0,1] neg_hi:[0,1]
	v_pk_add_f32 v[30:31], v[30:31], v[76:77] op_sel_hi:[1,0] neg_lo:[0,1] neg_hi:[0,1]
	v_pk_add_f32 v[32:33], v[32:33], v[76:77] op_sel_hi:[1,0] neg_lo:[0,1] neg_hi:[0,1]
	v_exp_f32_e32 v2, v2
	v_exp_f32_e32 v3, v3
	v_exp_f32_e32 v4, v4
	v_exp_f32_e32 v5, v5
	v_exp_f32_e32 v6, v6
	v_exp_f32_e32 v7, v7
	v_exp_f32_e32 v8, v8
	v_exp_f32_e32 v9, v9
	v_exp_f32_e32 v10, v10
	v_exp_f32_e32 v11, v11
	v_exp_f32_e32 v12, v12
	v_exp_f32_e32 v13, v13
	v_exp_f32_e32 v14, v14
	v_exp_f32_e32 v15, v15
	v_exp_f32_e32 v16, v16
	v_exp_f32_e32 v17, v17
	v_exp_f32_e32 v18, v18
	v_exp_f32_e32 v19, v19
	v_exp_f32_e32 v20, v20
	v_exp_f32_e32 v21, v21
	v_exp_f32_e32 v22, v22
	v_exp_f32_e32 v23, v23
	v_exp_f32_e32 v24, v24
	v_exp_f32_e32 v25, v25
	v_exp_f32_e32 v26, v26
	v_exp_f32_e32 v27, v27
	v_exp_f32_e32 v28, v28
	v_exp_f32_e32 v29, v29
	v_exp_f32_e32 v30, v30
	v_exp_f32_e32 v31, v31
	v_exp_f32_e32 v32, v32
	v_exp_f32_e32 v33, v33
	v_mul_f32_e32 v3, v70, v3
	v_mul_f32_e32 v5, v70, v5
	v_fmac_f32_e32 v3, v70, v2
	v_fma_f32 v2, v70, v4, v5
	v_add_f32_e32 v74, v3, v2
	v_mov_b32_e32 v75, v5
	s_nop 1
	v_permlane32_swap_b32_e32 v5, v75
	v_cndmask_b32_e64 v78, v5, v75, s[6:7]
	v_cndmask_b32_e64 v88, v78, v79, s[8:9]
	v_add_f32_e32 v74, v74, v88
	v_mov_b32_e32 v79, v78
	s_nop 0
	v_add_f32_dpp v89, v74, v74 quad_perm:[1,0,3,2] row_mask:0xf bank_mask:0xf bound_ctrl:1
	s_nop 1
	v_add_f32_dpp v80, v89, v89 quad_perm:[2,3,0,1] row_mask:0xf bank_mask:0xf bound_ctrl:1
	v_mul_f32_e32 v7, v70, v7
	v_mul_f32_e32 v9, v70, v9
	v_fmac_f32_e32 v7, v70, v6
	v_fma_f32 v6, v70, v8, v9
	v_add_f32_e32 v74, v7, v6
	v_mov_b32_e32 v75, v9
	s_nop 1
	v_permlane32_swap_b32_e32 v9, v75
	v_cndmask_b32_e64 v78, v9, v75, s[6:7]
	v_cndmask_b32_e64 v88, v78, v79, s[8:9]
	v_add_f32_e32 v74, v74, v88
	v_mov_b32_e32 v79, v78
	s_nop 0
	v_add_f32_dpp v89, v74, v74 quad_perm:[1,0,3,2] row_mask:0xf bank_mask:0xf bound_ctrl:1
	s_nop 1
	v_add_f32_dpp v81, v89, v89 quad_perm:[2,3,0,1] row_mask:0xf bank_mask:0xf bound_ctrl:1
	v_mul_f32_e32 v11, v70, v11
	v_mul_f32_e32 v13, v70, v13
	v_fmac_f32_e32 v11, v70, v10
	v_fma_f32 v10, v70, v12, v13
	v_add_f32_e32 v74, v11, v10
	v_mov_b32_e32 v75, v13
	s_nop 1
	v_permlane32_swap_b32_e32 v13, v75
	v_cndmask_b32_e64 v78, v13, v75, s[6:7]
	v_cndmask_b32_e64 v88, v78, v79, s[8:9]
	v_add_f32_e32 v74, v74, v88
	v_mov_b32_e32 v79, v78
	s_nop 0
	v_add_f32_dpp v89, v74, v74 quad_perm:[1,0,3,2] row_mask:0xf bank_mask:0xf bound_ctrl:1
	s_nop 1
	v_add_f32_dpp v82, v89, v89 quad_perm:[2,3,0,1] row_mask:0xf bank_mask:0xf bound_ctrl:1
	v_mul_f32_e32 v15, v70, v15
	v_mul_f32_e32 v17, v70, v17
	v_fmac_f32_e32 v15, v70, v14
	v_fma_f32 v14, v70, v16, v17
	v_add_f32_e32 v74, v15, v14
	v_mov_b32_e32 v75, v17
	s_nop 1
	v_permlane32_swap_b32_e32 v17, v75
	v_cndmask_b32_e64 v78, v17, v75, s[6:7]
	v_cndmask_b32_e64 v88, v78, v79, s[8:9]
	v_add_f32_e32 v74, v74, v88
	v_mov_b32_e32 v79, v78
	s_nop 0
	v_add_f32_dpp v89, v74, v74 quad_perm:[1,0,3,2] row_mask:0xf bank_mask:0xf bound_ctrl:1
	s_nop 1
	v_add_f32_dpp v83, v89, v89 quad_perm:[2,3,0,1] row_mask:0xf bank_mask:0xf bound_ctrl:1
	v_mul_f32_e32 v19, v70, v19
	v_mul_f32_e32 v21, v70, v21
	v_fmac_f32_e32 v19, v70, v18
	v_fma_f32 v18, v70, v20, v21
	v_add_f32_e32 v74, v19, v18
	v_mov_b32_e32 v75, v21
	s_nop 1
	v_permlane32_swap_b32_e32 v21, v75
	v_cndmask_b32_e64 v78, v21, v75, s[6:7]
	v_cndmask_b32_e64 v88, v78, v79, s[8:9]
	v_add_f32_e32 v74, v74, v88
	v_mov_b32_e32 v79, v78
	s_nop 0
	v_add_f32_dpp v89, v74, v74 quad_perm:[1,0,3,2] row_mask:0xf bank_mask:0xf bound_ctrl:1
	s_nop 1
	v_add_f32_dpp v84, v89, v89 quad_perm:[2,3,0,1] row_mask:0xf bank_mask:0xf bound_ctrl:1
	v_mul_f32_e32 v23, v70, v23
	v_mul_f32_e32 v25, v70, v25
	v_fmac_f32_e32 v23, v70, v22
	v_fma_f32 v22, v70, v24, v25
	v_add_f32_e32 v74, v23, v22
	v_mov_b32_e32 v75, v25
	s_nop 1
	v_permlane32_swap_b32_e32 v25, v75
	v_cndmask_b32_e64 v78, v25, v75, s[6:7]
	v_cndmask_b32_e64 v88, v78, v79, s[8:9]
	v_add_f32_e32 v74, v74, v88
	v_mov_b32_e32 v79, v78
	s_nop 0
	v_add_f32_dpp v89, v74, v74 quad_perm:[1,0,3,2] row_mask:0xf bank_mask:0xf bound_ctrl:1
	s_nop 1
	v_add_f32_dpp v85, v89, v89 quad_perm:[2,3,0,1] row_mask:0xf bank_mask:0xf bound_ctrl:1
	v_mul_f32_e32 v27, v70, v27
	v_mul_f32_e32 v29, v70, v29
	v_fmac_f32_e32 v27, v70, v26
	v_fma_f32 v26, v70, v28, v29
	v_add_f32_e32 v74, v27, v26
	v_mov_b32_e32 v75, v29
	s_nop 1
	v_permlane32_swap_b32_e32 v29, v75
	v_cndmask_b32_e64 v78, v29, v75, s[6:7]
	v_cndmask_b32_e64 v88, v78, v79, s[8:9]
	v_add_f32_e32 v74, v74, v88
	v_mov_b32_e32 v79, v78
	s_nop 0
	v_add_f32_dpp v89, v74, v74 quad_perm:[1,0,3,2] row_mask:0xf bank_mask:0xf bound_ctrl:1
	s_nop 1
	v_add_f32_dpp v86, v89, v89 quad_perm:[2,3,0,1] row_mask:0xf bank_mask:0xf bound_ctrl:1
	v_mul_f32_e32 v31, v70, v31
	v_mul_f32_e32 v33, v70, v33
	v_fmac_f32_e32 v31, v70, v30
	v_fma_f32 v30, v70, v32, v33
	v_add_f32_e32 v74, v31, v30
	v_mov_b32_e32 v75, v33
	s_nop 1
	v_permlane32_swap_b32_e32 v33, v75
	v_cndmask_b32_e64 v78, v33, v75, s[6:7]
	v_cndmask_b32_e64 v88, v78, v79, s[8:9]
	v_add_f32_e32 v74, v74, v88
	v_mov_b32_e32 v79, v78
	s_nop 0
	v_add_f32_dpp v89, v74, v74 quad_perm:[1,0,3,2] row_mask:0xf bank_mask:0xf bound_ctrl:1
	s_nop 1
	v_add_f32_dpp v87, v89, v89 quad_perm:[2,3,0,1] row_mask:0xf bank_mask:0xf bound_ctrl:1
	s_and_saveexec_b64 s[16:17], s[10:11]
	ds_write_b32 v91, v80
	ds_write_b32 v91, v81 offset:8
	ds_write_b32 v91, v82 offset:16
	ds_write_b32 v91, v83 offset:24
	ds_write_b32 v91, v84 offset:32
	ds_write_b32 v91, v85 offset:40
	ds_write_b32 v91, v86 offset:48
	ds_write_b32 v91, v87 offset:56
	s_or_b64 exec, exec, s[16:17]
	s_add_u32 s14, s14, 0x2000
	s_addc_u32 s15, s15, 0
	s_add_i32 s18, s18, 64
	v_add_u32_e32 v161, 0xfffffc00, v161
	s_cmp_lg_u32 s24, 0
	s_cbranch_scc1 .Lc2_loop
	v_mov_b32_e32 v73, v79
	s_branch .LBB0_1292
